# phase 0 x f32->bf16 row loop: 3-row-deep load pipeline (was 2 serialized round trips per row)
# speedup vs baseline: 1.0009x; 1.0009x over previous
.LBB0_17:
	s_or_b64 exec, exec, s[6:7]
	s_mov_b64 s[0:1], s[86:87]
	s_load_dwordx4 s[8:11], s[0:1], 0x0
	s_load_dwordx2 s[16:17], s[0:1], 0x30
	s_load_dwordx2 s[24:25], s[0:1], 0x50
	s_load_dwordx2 s[26:27], s[0:1], 0x60
	s_load_dwordx4 s[12:15], s[0:1], 0x70
	s_load_dwordx2 s[18:19], s[0:1], 0x98
	s_load_dwordx2 s[6:7], s[0:1], 0xb8
	v_mov_b32_e32 v8, v204
	s_lshl_b32 s94, s97, 3
	v_ashrrev_i32_e32 v0, 6, v8
	v_add_u32_e32 v0, s94, v0
	s_mov_b32 s0, 0x8000
	v_cmp_gt_i32_e32 vcc, s0, v0
	v_mbcnt_lo_u32_b32 v152, -1, 0
	s_and_saveexec_b64 s[28:29], vcc
	s_cbranch_execz .LBB0_22
	v_and_b32_e32 v1, 63, v8
	v_lshlrev_b32_e32 v4, 4, v1
	v_mov_b32_e32 v5, 0
	s_waitcnt lgkmcnt(0)
	v_lshl_add_u64 v[2:3], s[6:7], 0, v[4:5]
	v_mbcnt_hi_u32_b32 v4, -1, v152
	v_and_b32_e32 v6, 64, v4
	v_add_u32_e32 v12, 64, v6
	v_xor_b32_e32 v6, 32, v4
	v_cmp_lt_i32_e64 s[4:5], v6, v12
	v_xor_b32_e32 v7, 16, v4
	v_xor_b32_e32 v9, 8, v4
	v_cndmask_b32_e64 v6, v4, v6, s[4:5]
	v_cmp_lt_i32_e64 s[4:5], v7, v12
	v_xor_b32_e32 v10, 4, v4
	v_xor_b32_e32 v11, 2, v4
	v_cndmask_b32_e64 v7, v4, v7, s[4:5]
	v_cmp_lt_i32_e64 s[4:5], v9, v12
	v_xor_b32_e32 v13, 1, v4
	s_add_u32 s30, s6, 0x1fe00000
	v_cndmask_b32_e64 v9, v4, v9, s[4:5]
	v_cmp_lt_i32_e64 s[4:5], v10, v12
	s_mov_b64 s[0:1], 0x3a00000
	s_addc_u32 s31, s7, 0
	v_cndmask_b32_e64 v10, v4, v10, s[4:5]
	v_cmp_lt_i32_e64 s[4:5], v11, v12
	v_lshl_add_u64 v[2:3], v[2:3], 0, s[0:1]
	v_cmp_eq_u32_e32 vcc, 0, v1
	v_cndmask_b32_e64 v11, v4, v11, s[4:5]
	v_cmp_lt_i32_e64 s[4:5], v13, v12
	s_lshl_b32 s0, s22, 3
	v_lshlrev_b32_e32 v6, 2, v6
	v_cndmask_b32_e64 v4, v4, v13, s[4:5]
	v_lshlrev_b32_e32 v12, 2, v4
	v_lshlrev_b32_e32 v4, 5, v1
	v_lshlrev_b32_e32 v7, 2, v7
	v_lshlrev_b32_e32 v9, 2, v9
	v_lshlrev_b32_e32 v10, 2, v10
	v_lshlrev_b32_e32 v11, 2, v11
	v_lshl_add_u64 v[4:5], s[8:9], 0, v[4:5]
	s_mov_b64 s[8:9], 0
	s_movk_i32 s1, 0x7fff
	s_branch .LBB0_20


.LBB0_20:
	s_nop 1
	v_readfirstlane_b32 s32, v0
	s_nop 0
	s_mov_b32 s33, s32
	s_mov_b32 s40, s32
	s_mov_b32 s41, 0
	s_lshl_b64 s[40:41], s[40:41], 12
	v_lshl_add_u64 v[20:21], v[4:5], 0, s[40:41]
	global_load_dwordx4 v[40:43], v[20:21], off
	global_load_dwordx4 v[44:47], v[20:21], off offset:16
	global_load_dwordx4 v[48:51], v[20:21], off offset:2048
	global_load_dwordx4 v[52:55], v[20:21], off offset:2064
	s_add_u32 s40, s32, s0
	s_cmp_gt_u32 s40, s1
	s_cselect_b32 s40, s33, s40
	s_mov_b32 s41, 0
	s_lshl_b64 s[40:41], s[40:41], 12
	v_lshl_add_u64 v[20:21], v[4:5], 0, s[40:41]
	global_load_dwordx4 v[56:59], v[20:21], off
	global_load_dwordx4 v[60:63], v[20:21], off offset:16
	global_load_dwordx4 v[64:67], v[20:21], off offset:2048
	global_load_dwordx4 v[68:71], v[20:21], off offset:2064
	s_lshl_b32 s40, s0, 1
	s_add_u32 s40, s32, s40
	s_cmp_gt_u32 s40, s1
	s_cselect_b32 s40, s33, s40
	s_mov_b32 s41, 0
	s_lshl_b64 s[40:41], s[40:41], 12
	v_lshl_add_u64 v[20:21], v[4:5], 0, s[40:41]
	global_load_dwordx4 v[72:75], v[20:21], off
	global_load_dwordx4 v[76:79], v[20:21], off offset:16
	global_load_dwordx4 v[80:83], v[20:21], off offset:2048
	global_load_dwordx4 v[84:87], v[20:21], off offset:2064
	s_waitcnt vmcnt(8)
	s_mov_b32 s42, s32
	s_mov_b32 s43, 0
	s_lshl_b64 s[44:45], s[42:43], 11
	v_lshl_add_u64 v[32:33], v[2:3], 0, s[44:45]
	v_cvt_pk_bf16_f32 v22, v40, v41
	v_cvt_pk_bf16_f32 v23, v42, v43
	v_cvt_pk_bf16_f32 v24, v44, v45
	v_cvt_pk_bf16_f32 v25, v46, v47
	global_store_dwordx4 v[32:33], v[22:25], off
	v_mul_f32_e32 v13, v41, v41
	v_fmac_f32_e32 v13, v40, v40
	v_fmac_f32_e32 v13, v42, v42
	v_fmac_f32_e32 v13, v43, v43
	v_fmac_f32_e32 v13, v44, v44
	v_fmac_f32_e32 v13, v45, v45
	v_fmac_f32_e32 v13, v46, v46
	v_fmac_f32_e32 v13, v47, v47
	v_mul_f32_e32 v14, v49, v49
	v_fmac_f32_e32 v14, v48, v48
	v_fmac_f32_e32 v14, v50, v50
	v_fmac_f32_e32 v14, v51, v51
	v_fmac_f32_e32 v14, v52, v52
	v_fmac_f32_e32 v14, v53, v53
	v_fmac_f32_e32 v14, v54, v54
	v_fmac_f32_e32 v14, v55, v55
	v_add_f32_e32 v13, v13, v14
	ds_bpermute_b32 v14, v6, v13
	v_cvt_pk_bf16_f32 v16, v48, v49
	v_cvt_pk_bf16_f32 v17, v50, v51
	v_cvt_pk_bf16_f32 v18, v52, v53
	v_cvt_pk_bf16_f32 v19, v54, v55
	s_waitcnt lgkmcnt(0)
	v_add_f32_e32 v13, v13, v14
	ds_bpermute_b32 v14, v7, v13
	global_store_dwordx4 v[32:33], v[16:19], off offset:1024
	s_waitcnt lgkmcnt(0)
	v_add_f32_e32 v13, v13, v14
	ds_bpermute_b32 v14, v9, v13
	s_waitcnt lgkmcnt(0)
	v_add_f32_e32 v13, v13, v14
	ds_bpermute_b32 v14, v10, v13
	s_waitcnt lgkmcnt(0)
	v_add_f32_e32 v13, v13, v14
	ds_bpermute_b32 v14, v11, v13
	s_waitcnt lgkmcnt(0)
	v_add_f32_e32 v13, v13, v14
	ds_bpermute_b32 v14, v12, v13
	v_mov_b32_e32 v34, s32
	v_mov_b32_e32 v35, 0
	s_waitcnt lgkmcnt(0)
	s_and_saveexec_b64 s[4:5], vcc
	v_add_f32_e32 v13, v13, v14
	v_mul_f32_e32 v13, 0x4b800000, v13
	v_trunc_f32_e32 v13, v13
	v_mul_f32_e32 v14, 0x2f800000, v13
	v_floor_f32_e32 v15, v14
	v_fmac_f32_e32 v13, 0xcf800000, v15
	v_cvt_u32_f32_e32 v14, v13
	v_cvt_u32_f32_e32 v15, v15
	v_lshl_add_u64 v[36:37], v[34:35], 3, s[30:31]
	global_store_dwordx2 v[36:37], v[14:15], off
	s_or_b64 exec, exec, s[4:5]
	s_add_u32 s32, s32, s0
	s_cmp_gt_u32 s32, s1
	s_cbranch_scc1 .Lp0x_done
	s_lshl_b32 s40, s0, 1
	s_add_u32 s40, s32, s40
	s_cmp_gt_u32 s40, s1
	s_cselect_b32 s40, s33, s40
	s_mov_b32 s41, 0
	s_lshl_b64 s[40:41], s[40:41], 12
	v_lshl_add_u64 v[20:21], v[4:5], 0, s[40:41]
	global_load_dwordx4 v[40:43], v[20:21], off
	global_load_dwordx4 v[44:47], v[20:21], off offset:16
	global_load_dwordx4 v[48:51], v[20:21], off offset:2048
	global_load_dwordx4 v[52:55], v[20:21], off offset:2064
	s_waitcnt vmcnt(11)
	s_mov_b32 s42, s32
	s_mov_b32 s43, 0
	s_lshl_b64 s[44:45], s[42:43], 11
	v_lshl_add_u64 v[32:33], v[2:3], 0, s[44:45]
	v_cvt_pk_bf16_f32 v22, v56, v57
	v_cvt_pk_bf16_f32 v23, v58, v59
	v_cvt_pk_bf16_f32 v24, v60, v61
	v_cvt_pk_bf16_f32 v25, v62, v63
	global_store_dwordx4 v[32:33], v[22:25], off
	v_mul_f32_e32 v13, v57, v57
	v_fmac_f32_e32 v13, v56, v56
	v_fmac_f32_e32 v13, v58, v58
	v_fmac_f32_e32 v13, v59, v59
	v_fmac_f32_e32 v13, v60, v60
	v_fmac_f32_e32 v13, v61, v61
	v_fmac_f32_e32 v13, v62, v62
	v_fmac_f32_e32 v13, v63, v63
	v_mul_f32_e32 v14, v65, v65
	v_fmac_f32_e32 v14, v64, v64
	v_fmac_f32_e32 v14, v66, v66
	v_fmac_f32_e32 v14, v67, v67
	v_fmac_f32_e32 v14, v68, v68
	v_fmac_f32_e32 v14, v69, v69
	v_fmac_f32_e32 v14, v70, v70
	v_fmac_f32_e32 v14, v71, v71
	v_add_f32_e32 v13, v13, v14
	ds_bpermute_b32 v14, v6, v13
	v_cvt_pk_bf16_f32 v16, v64, v65
	v_cvt_pk_bf16_f32 v17, v66, v67
	v_cvt_pk_bf16_f32 v18, v68, v69
	v_cvt_pk_bf16_f32 v19, v70, v71
	s_waitcnt lgkmcnt(0)
	v_add_f32_e32 v13, v13, v14
	ds_bpermute_b32 v14, v7, v13
	global_store_dwordx4 v[32:33], v[16:19], off offset:1024
	s_waitcnt lgkmcnt(0)
	v_add_f32_e32 v13, v13, v14
	ds_bpermute_b32 v14, v9, v13
	s_waitcnt lgkmcnt(0)
	v_add_f32_e32 v13, v13, v14
	ds_bpermute_b32 v14, v10, v13
	s_waitcnt lgkmcnt(0)
	v_add_f32_e32 v13, v13, v14
	ds_bpermute_b32 v14, v11, v13
	s_waitcnt lgkmcnt(0)
	v_add_f32_e32 v13, v13, v14
	ds_bpermute_b32 v14, v12, v13
	v_mov_b32_e32 v34, s32
	v_mov_b32_e32 v35, 0
	s_waitcnt lgkmcnt(0)
	s_and_saveexec_b64 s[4:5], vcc
	v_add_f32_e32 v13, v13, v14
	v_mul_f32_e32 v13, 0x4b800000, v13
	v_trunc_f32_e32 v13, v13
	v_mul_f32_e32 v14, 0x2f800000, v13
	v_floor_f32_e32 v15, v14
	v_fmac_f32_e32 v13, 0xcf800000, v15
	v_cvt_u32_f32_e32 v14, v13
	v_cvt_u32_f32_e32 v15, v15
	v_lshl_add_u64 v[36:37], v[34:35], 3, s[30:31]
	global_store_dwordx2 v[36:37], v[14:15], off
	s_or_b64 exec, exec, s[4:5]
	s_add_u32 s32, s32, s0
	s_cmp_gt_u32 s32, s1
	s_cbranch_scc1 .Lp0x_done
.Lp0x_loop:
	s_lshl_b32 s40, s0, 1
	s_add_u32 s40, s32, s40
	s_cmp_gt_u32 s40, s1
	s_cselect_b32 s40, s33, s40
	s_mov_b32 s41, 0
	s_lshl_b64 s[40:41], s[40:41], 12
	v_lshl_add_u64 v[20:21], v[4:5], 0, s[40:41]
	global_load_dwordx4 v[56:59], v[20:21], off
	global_load_dwordx4 v[60:63], v[20:21], off offset:16
	global_load_dwordx4 v[64:67], v[20:21], off offset:2048
	global_load_dwordx4 v[68:71], v[20:21], off offset:2064
	s_waitcnt vmcnt(14)
	s_mov_b32 s42, s32
	s_mov_b32 s43, 0
	s_lshl_b64 s[44:45], s[42:43], 11
	v_lshl_add_u64 v[32:33], v[2:3], 0, s[44:45]
	v_cvt_pk_bf16_f32 v22, v72, v73
	v_cvt_pk_bf16_f32 v23, v74, v75
	v_cvt_pk_bf16_f32 v24, v76, v77
	v_cvt_pk_bf16_f32 v25, v78, v79
	global_store_dwordx4 v[32:33], v[22:25], off
	v_mul_f32_e32 v13, v73, v73
	v_fmac_f32_e32 v13, v72, v72
	v_fmac_f32_e32 v13, v74, v74
	v_fmac_f32_e32 v13, v75, v75
	v_fmac_f32_e32 v13, v76, v76
	v_fmac_f32_e32 v13, v77, v77
	v_fmac_f32_e32 v13, v78, v78
	v_fmac_f32_e32 v13, v79, v79
	v_mul_f32_e32 v14, v81, v81
	v_fmac_f32_e32 v14, v80, v80
	v_fmac_f32_e32 v14, v82, v82
	v_fmac_f32_e32 v14, v83, v83
	v_fmac_f32_e32 v14, v84, v84
	v_fmac_f32_e32 v14, v85, v85
	v_fmac_f32_e32 v14, v86, v86
	v_fmac_f32_e32 v14, v87, v87
	v_add_f32_e32 v13, v13, v14
	ds_bpermute_b32 v14, v6, v13
	v_cvt_pk_bf16_f32 v16, v80, v81
	v_cvt_pk_bf16_f32 v17, v82, v83
	v_cvt_pk_bf16_f32 v18, v84, v85
	v_cvt_pk_bf16_f32 v19, v86, v87
	s_waitcnt lgkmcnt(0)
	v_add_f32_e32 v13, v13, v14
	ds_bpermute_b32 v14, v7, v13
	global_store_dwordx4 v[32:33], v[16:19], off offset:1024
	s_waitcnt lgkmcnt(0)
	v_add_f32_e32 v13, v13, v14
	ds_bpermute_b32 v14, v9, v13
	s_waitcnt lgkmcnt(0)
	v_add_f32_e32 v13, v13, v14
	ds_bpermute_b32 v14, v10, v13
	s_waitcnt lgkmcnt(0)
	v_add_f32_e32 v13, v13, v14
	ds_bpermute_b32 v14, v11, v13
	s_waitcnt lgkmcnt(0)
	v_add_f32_e32 v13, v13, v14
	ds_bpermute_b32 v14, v12, v13
	v_mov_b32_e32 v34, s32
	v_mov_b32_e32 v35, 0
	s_waitcnt lgkmcnt(0)
	s_and_saveexec_b64 s[4:5], vcc
	v_add_f32_e32 v13, v13, v14
	v_mul_f32_e32 v13, 0x4b800000, v13
	v_trunc_f32_e32 v13, v13
	v_mul_f32_e32 v14, 0x2f800000, v13
	v_floor_f32_e32 v15, v14
	v_fmac_f32_e32 v13, 0xcf800000, v15
	v_cvt_u32_f32_e32 v14, v13
	v_cvt_u32_f32_e32 v15, v15
	v_lshl_add_u64 v[36:37], v[34:35], 3, s[30:31]
	global_store_dwordx2 v[36:37], v[14:15], off
	s_or_b64 exec, exec, s[4:5]
	s_add_u32 s32, s32, s0
	s_cmp_gt_u32 s32, s1
	s_cbranch_scc1 .Lp0x_done
	s_lshl_b32 s40, s0, 1
	s_add_u32 s40, s32, s40
	s_cmp_gt_u32 s40, s1
	s_cselect_b32 s40, s33, s40
	s_mov_b32 s41, 0
	s_lshl_b64 s[40:41], s[40:41], 12
	v_lshl_add_u64 v[20:21], v[4:5], 0, s[40:41]
	global_load_dwordx4 v[72:75], v[20:21], off
	global_load_dwordx4 v[76:79], v[20:21], off offset:16
	global_load_dwordx4 v[80:83], v[20:21], off offset:2048
	global_load_dwordx4 v[84:87], v[20:21], off offset:2064
	s_waitcnt vmcnt(14)
	s_mov_b32 s42, s32
	s_mov_b32 s43, 0
	s_lshl_b64 s[44:45], s[42:43], 11
	v_lshl_add_u64 v[32:33], v[2:3], 0, s[44:45]
	v_cvt_pk_bf16_f32 v22, v40, v41
	v_cvt_pk_bf16_f32 v23, v42, v43
	v_cvt_pk_bf16_f32 v24, v44, v45
	v_cvt_pk_bf16_f32 v25, v46, v47
	global_store_dwordx4 v[32:33], v[22:25], off
	v_mul_f32_e32 v13, v41, v41
	v_fmac_f32_e32 v13, v40, v40
	v_fmac_f32_e32 v13, v42, v42
	v_fmac_f32_e32 v13, v43, v43
	v_fmac_f32_e32 v13, v44, v44
	v_fmac_f32_e32 v13, v45, v45
	v_fmac_f32_e32 v13, v46, v46
	v_fmac_f32_e32 v13, v47, v47
	v_mul_f32_e32 v14, v49, v49
	v_fmac_f32_e32 v14, v48, v48
	v_fmac_f32_e32 v14, v50, v50
	v_fmac_f32_e32 v14, v51, v51
	v_fmac_f32_e32 v14, v52, v52
	v_fmac_f32_e32 v14, v53, v53
	v_fmac_f32_e32 v14, v54, v54
	v_fmac_f32_e32 v14, v55, v55
	v_add_f32_e32 v13, v13, v14
	ds_bpermute_b32 v14, v6, v13
	v_cvt_pk_bf16_f32 v16, v48, v49
	v_cvt_pk_bf16_f32 v17, v50, v51
	v_cvt_pk_bf16_f32 v18, v52, v53
	v_cvt_pk_bf16_f32 v19, v54, v55
	s_waitcnt lgkmcnt(0)
	v_add_f32_e32 v13, v13, v14
	ds_bpermute_b32 v14, v7, v13
	global_store_dwordx4 v[32:33], v[16:19], off offset:1024
	s_waitcnt lgkmcnt(0)
	v_add_f32_e32 v13, v13, v14
	ds_bpermute_b32 v14, v9, v13
	s_waitcnt lgkmcnt(0)
	v_add_f32_e32 v13, v13, v14
	ds_bpermute_b32 v14, v10, v13
	s_waitcnt lgkmcnt(0)
	v_add_f32_e32 v13, v13, v14
	ds_bpermute_b32 v14, v11, v13
	s_waitcnt lgkmcnt(0)
	v_add_f32_e32 v13, v13, v14
	ds_bpermute_b32 v14, v12, v13
	v_mov_b32_e32 v34, s32
	v_mov_b32_e32 v35, 0
	s_waitcnt lgkmcnt(0)
	s_and_saveexec_b64 s[4:5], vcc
	v_add_f32_e32 v13, v13, v14
	v_mul_f32_e32 v13, 0x4b800000, v13
	v_trunc_f32_e32 v13, v13
	v_mul_f32_e32 v14, 0x2f800000, v13
	v_floor_f32_e32 v15, v14
	v_fmac_f32_e32 v13, 0xcf800000, v15
	v_cvt_u32_f32_e32 v14, v13
	v_cvt_u32_f32_e32 v15, v15
	v_lshl_add_u64 v[36:37], v[34:35], 3, s[30:31]
	global_store_dwordx2 v[36:37], v[14:15], off
	s_or_b64 exec, exec, s[4:5]
	s_add_u32 s32, s32, s0
	s_cmp_gt_u32 s32, s1
	s_cbranch_scc1 .Lp0x_done
	s_lshl_b32 s40, s0, 1
	s_add_u32 s40, s32, s40
	s_cmp_gt_u32 s40, s1
	s_cselect_b32 s40, s33, s40
	s_mov_b32 s41, 0
	s_lshl_b64 s[40:41], s[40:41], 12
	v_lshl_add_u64 v[20:21], v[4:5], 0, s[40:41]
	global_load_dwordx4 v[40:43], v[20:21], off
	global_load_dwordx4 v[44:47], v[20:21], off offset:16
	global_load_dwordx4 v[48:51], v[20:21], off offset:2048
	global_load_dwordx4 v[52:55], v[20:21], off offset:2064
	s_waitcnt vmcnt(14)
	s_mov_b32 s42, s32
	s_mov_b32 s43, 0
	s_lshl_b64 s[44:45], s[42:43], 11
	v_lshl_add_u64 v[32:33], v[2:3], 0, s[44:45]
	v_cvt_pk_bf16_f32 v22, v56, v57
	v_cvt_pk_bf16_f32 v23, v58, v59
	v_cvt_pk_bf16_f32 v24, v60, v61
	v_cvt_pk_bf16_f32 v25, v62, v63
	global_store_dwordx4 v[32:33], v[22:25], off
	v_mul_f32_e32 v13, v57, v57
	v_fmac_f32_e32 v13, v56, v56
	v_fmac_f32_e32 v13, v58, v58
	v_fmac_f32_e32 v13, v59, v59
	v_fmac_f32_e32 v13, v60, v60
	v_fmac_f32_e32 v13, v61, v61
	v_fmac_f32_e32 v13, v62, v62
	v_fmac_f32_e32 v13, v63, v63
	v_mul_f32_e32 v14, v65, v65
	v_fmac_f32_e32 v14, v64, v64
	v_fmac_f32_e32 v14, v66, v66
	v_fmac_f32_e32 v14, v67, v67
	v_fmac_f32_e32 v14, v68, v68
	v_fmac_f32_e32 v14, v69, v69
	v_fmac_f32_e32 v14, v70, v70
	v_fmac_f32_e32 v14, v71, v71
	v_add_f32_e32 v13, v13, v14
	ds_bpermute_b32 v14, v6, v13
	v_cvt_pk_bf16_f32 v16, v64, v65
	v_cvt_pk_bf16_f32 v17, v66, v67
	v_cvt_pk_bf16_f32 v18, v68, v69
	v_cvt_pk_bf16_f32 v19, v70, v71
	s_waitcnt lgkmcnt(0)
	v_add_f32_e32 v13, v13, v14
	ds_bpermute_b32 v14, v7, v13
	global_store_dwordx4 v[32:33], v[16:19], off offset:1024
	s_waitcnt lgkmcnt(0)
	v_add_f32_e32 v13, v13, v14
	ds_bpermute_b32 v14, v9, v13
	s_waitcnt lgkmcnt(0)
	v_add_f32_e32 v13, v13, v14
	ds_bpermute_b32 v14, v10, v13
	s_waitcnt lgkmcnt(0)
	v_add_f32_e32 v13, v13, v14
	ds_bpermute_b32 v14, v11, v13
	s_waitcnt lgkmcnt(0)
	v_add_f32_e32 v13, v13, v14
	ds_bpermute_b32 v14, v12, v13
	v_mov_b32_e32 v34, s32
	v_mov_b32_e32 v35, 0
	s_waitcnt lgkmcnt(0)
	s_and_saveexec_b64 s[4:5], vcc
	v_add_f32_e32 v13, v13, v14
	v_mul_f32_e32 v13, 0x4b800000, v13
	v_trunc_f32_e32 v13, v13
	v_mul_f32_e32 v14, 0x2f800000, v13
	v_floor_f32_e32 v15, v14
	v_fmac_f32_e32 v13, 0xcf800000, v15
	v_cvt_u32_f32_e32 v14, v13
	v_cvt_u32_f32_e32 v15, v15
	v_lshl_add_u64 v[36:37], v[34:35], 3, s[30:31]
	global_store_dwordx2 v[36:37], v[14:15], off
	s_or_b64 exec, exec, s[4:5]
	s_add_u32 s32, s32, s0
	s_cmp_gt_u32 s32, s1
	s_cbranch_scc1 .Lp0x_done
	s_branch .Lp0x_loop
.Lp0x_done:
	s_waitcnt vmcnt(0)
	s_branch .LBB0_22


